# gdn_prep beta stage: dt_bias / a_log per-head scalars fetched at item start instead of two exposed global loads inside the one-wave stage
# speedup vs baseline: 1.0113x; 1.0002x over previous
; DI float bf2f(bf16_t v) { return __uint_as_float(((unsigned)v) << 16); }
; DI float siluf_(float x) { return x / (1.f + __expf(-x)); }
; DI void phase_gdn_prep(const Params& p, int l, char* smem) {
;     ...
;         {
;             bf16_t* sraw = (bf16_t*)sL;
;             const int ch = tid & 63, tq = tid >> 6;
; #pragma unroll
;             for (int part = 0; part < 3; ++part) {
; #pragma unroll
;                 for (int k = 0; k < 3; ++k) { const int c = tid + 256 * k; if (c < 67 * 8) *(u32x4*)(sraw + c * 8) = raw[part * 3 + k]; }
;                 __syncthreads();
;                 const int col = part * 384 + h * 64 + ch;
;                 const float w0 = cw[col], w1 = cw[1152 + col], w2 = cw[2 * 1152 + col], w3 = cw[3 * 1152 + col];
;                 float* dst = part == 0 ? sq : (part == 1 ? sk : sv);
; #pragma unroll
;                 for (int i = 0; i < 16; ++i) {
;                     const int t = tq + 4 * i;
;                     const float x0 = bf2f(sraw[(t + 0) * 64 + ch]), x1 = bf2f(sraw[(t + 1) * 64 + ch]);
;                     const float x2 = bf2f(sraw[(t + 2) * 64 + ch]), x3 = bf2f(sraw[(t + 3) * 64 + ch]);
;                     const float a = x0 * w0 + x1 * w1 + x2 * w2 + x3 * w3;
;                     dst[t * 65 + ch] = siluf_(a);
;                 }
;                 __syncthreads();
;             }
;         }
.LBB0_268:
	s_or_b64 exec, exec, s[4:5]
	s_ashr_i32 s4, s86, 8
	s_mul_hi_i32 s5, s4, 0x2aaaaaab
	s_lshr_b32 s6, s5, 31
	s_add_i32 s5, s5, s6
	s_mul_i32 s5, s5, 6
	s_sub_i32 s6, s4, s5
	s_waitcnt vmcnt(4)
	v_lshl_or_b32 v24, s6, 6, v62
	v_ashrrev_i32_e32 v25, 31, v24
	v_lshl_add_u64 v[24:25], v[24:25], 2, s[40:41]
	v_add_co_u32_e32 v28, vcc, s35, v24
	s_waitcnt lgkmcnt(0)
	s_nop 0
	v_addc_co_u32_e32 v29, vcc, 0, v25, vcc
	s_barrier
	s_mul_i32 s98, s77, 6
	s_add_i32 s98, s6, s98
	s_lshl_b32 s98, s98, 2
	v_readlane_b32 s100, v251, 28
	v_readlane_b32 s101, v251, 29
	s_nop 0
	s_add_u32 s100, s100, s98
	s_addc_u32 s101, s101, 0
	global_load_dword v108, v189, s[100:101]
	v_readlane_b32 s100, v251, 26
	v_readlane_b32 s101, v251, 27
	s_nop 0
	s_add_u32 s100, s100, s98
	s_addc_u32 s101, s101, 0
	global_load_dword v109, v189, s[100:101]
	global_load_dword v37, v[24:25], off
	global_load_dword v58, v[24:25], off offset:1536
	global_load_dword v76, v[24:25], off offset:3072
	v_add_co_u32_e32 v208, vcc, 0x1200, v24
	s_nop 1
	v_addc_co_u32_e32 v209, vcc, 0, v25, vcc
	global_load_dword v38, v[208:209], off
	global_load_dword v59, v[208:209], off offset:1536
	global_load_dword v185, v[208:209], off offset:3072
	v_add_co_u32_e32 v208, vcc, 0x1200, v208
	s_nop 1
	v_addc_co_u32_e32 v209, vcc, 0, v209, vcc
	global_load_dword v39, v[208:209], off
	global_load_dword v60, v[208:209], off offset:1536
	global_load_dword v186, v[208:209], off offset:3072
	v_add_co_u32_e32 v208, vcc, 0x1200, v208
	s_nop 1
	v_addc_co_u32_e32 v209, vcc, 0, v209, vcc
	global_load_dword v54, v[208:209], off
	global_load_dword v61, v[208:209], off offset:1536
	global_load_dword v187, v[208:209], off offset:3072
	ds_read_u16 v191, v78 offset:49920
	ds_read_u16 v192, v78 offset:50048
	ds_read_u16 v193, v78 offset:50176
	ds_read_u16 v194, v78 offset:50304
	ds_read_u16 v195, v78 offset:50432
	ds_read_u16 v196, v78 offset:50560
	ds_read_u16 v197, v78 offset:50688
	ds_read_u16 v198, v78 offset:50816
	ds_read_u16 v199, v78 offset:50944
	ds_read_u16 v200, v78 offset:51072
	ds_read_u16 v201, v78 offset:51200
	ds_read_u16 v202, v78 offset:51328
	ds_read_u16 v203, v78 offset:51456
	ds_read_u16 v204, v78 offset:51584
	ds_read_u16 v205, v78 offset:51712
	ds_read_u16 v206, v78 offset:51840
	s_waitcnt vmcnt(0)
	s_waitcnt lgkmcnt(0)
	v_lshlrev_b32_e32 v191, 16, v191
	v_lshlrev_b32_e32 v192, 16, v192
	v_lshlrev_b32_e32 v193, 16, v193
	v_lshlrev_b32_e32 v194, 16, v194
	v_mul_f32_e32 v230, v38, v192
	v_fmac_f32_e32 v230, v37, v191
	v_fmac_f32_e32 v230, v39, v193
	v_fmac_f32_e32 v230, v54, v194
	v_lshlrev_b32_e32 v195, 16, v195
	v_lshlrev_b32_e32 v196, 16, v196
	v_lshlrev_b32_e32 v197, 16, v197
	v_lshlrev_b32_e32 v198, 16, v198
	v_mul_f32_e32 v231, v38, v196
	v_fmac_f32_e32 v231, v37, v195
	v_fmac_f32_e32 v231, v39, v197
	v_fmac_f32_e32 v231, v54, v198
	v_lshlrev_b32_e32 v199, 16, v199
	v_lshlrev_b32_e32 v200, 16, v200
	v_lshlrev_b32_e32 v201, 16, v201
	v_lshlrev_b32_e32 v202, 16, v202
	v_mul_f32_e32 v232, v38, v200
	v_fmac_f32_e32 v232, v37, v199
	v_fmac_f32_e32 v232, v39, v201
	v_fmac_f32_e32 v232, v54, v202
	v_lshlrev_b32_e32 v203, 16, v203
	v_lshlrev_b32_e32 v204, 16, v204
	v_lshlrev_b32_e32 v205, 16, v205
	v_lshlrev_b32_e32 v206, 16, v206
	v_mul_f32_e32 v233, v38, v204
	v_fmac_f32_e32 v233, v37, v203
	v_fmac_f32_e32 v233, v39, v205
	v_fmac_f32_e32 v233, v54, v206
	ds_read_u16 v191, v78 offset:51968
	ds_read_u16 v192, v78 offset:52096
	ds_read_u16 v193, v78 offset:52224
	ds_read_u16 v194, v78 offset:52352
	ds_read_u16 v195, v78 offset:52480
	ds_read_u16 v196, v78 offset:52608
	ds_read_u16 v197, v78 offset:52736
	ds_read_u16 v198, v78 offset:52864
	ds_read_u16 v199, v78 offset:52992
	ds_read_u16 v200, v78 offset:53120
	ds_read_u16 v201, v78 offset:53248
	ds_read_u16 v202, v78 offset:53376
	ds_read_u16 v203, v78 offset:53504
	ds_read_u16 v204, v78 offset:53632
	ds_read_u16 v205, v78 offset:53760
	ds_read_u16 v206, v78 offset:53888
	v_mul_f32_e32 v234, 0xbfb8aa3b, v230
	v_exp_f32_e32 v234, v234
	s_nop 0
	v_add_f32_e32 v234, 1.0, v234
	v_div_scale_f32 v235, s[4:5], v234, v234, v230
	v_rcp_f32_e32 v236, v235
	s_nop 0
	v_fma_f32 v237, -v235, v236, 1.0
	v_fmac_f32_e32 v236, v237, v236
	v_div_scale_f32 v237, vcc, v230, v234, v230
	v_mul_f32_e32 v238, v237, v236
	v_fma_f32 v239, -v235, v238, v237
	v_fmac_f32_e32 v238, v239, v236
	v_fma_f32 v235, -v235, v238, v237
	v_div_fmas_f32 v235, v235, v236, v238
	v_div_fixup_f32 v234, v235, v234, v230
	ds_write_b32 v173, v234
	v_mul_f32_e32 v234, 0xbfb8aa3b, v231
	v_exp_f32_e32 v234, v234
	s_nop 0
	v_add_f32_e32 v234, 1.0, v234
	v_div_scale_f32 v235, s[4:5], v234, v234, v231
	v_rcp_f32_e32 v236, v235
	s_nop 0
	v_fma_f32 v237, -v235, v236, 1.0
	v_fmac_f32_e32 v236, v237, v236
	v_div_scale_f32 v237, vcc, v231, v234, v231
	v_mul_f32_e32 v238, v237, v236
	v_fma_f32 v239, -v235, v238, v237
	v_fmac_f32_e32 v238, v239, v236
	v_fma_f32 v235, -v235, v238, v237
	v_div_fmas_f32 v235, v235, v236, v238
	v_div_fixup_f32 v234, v235, v234, v231
	ds_write_b32 v173, v234 offset:1040
	v_mul_f32_e32 v234, 0xbfb8aa3b, v232
	v_exp_f32_e32 v234, v234
	s_nop 0
	v_add_f32_e32 v234, 1.0, v234
	v_div_scale_f32 v235, s[4:5], v234, v234, v232
	v_rcp_f32_e32 v236, v235
	s_nop 0
	v_fma_f32 v237, -v235, v236, 1.0
	v_fmac_f32_e32 v236, v237, v236
	v_div_scale_f32 v237, vcc, v232, v234, v232
	v_mul_f32_e32 v238, v237, v236
	v_fma_f32 v239, -v235, v238, v237
	v_fmac_f32_e32 v238, v239, v236
	v_fma_f32 v235, -v235, v238, v237
	v_div_fmas_f32 v235, v235, v236, v238
	v_div_fixup_f32 v234, v235, v234, v232
	ds_write_b32 v173, v234 offset:2080
	v_mul_f32_e32 v234, 0xbfb8aa3b, v233
	v_exp_f32_e32 v234, v234
	s_nop 0
	v_add_f32_e32 v234, 1.0, v234
	v_div_scale_f32 v235, s[4:5], v234, v234, v233
	v_rcp_f32_e32 v236, v235
	s_nop 0
	v_fma_f32 v237, -v235, v236, 1.0
	v_fmac_f32_e32 v236, v237, v236
	v_div_scale_f32 v237, vcc, v233, v234, v233
	v_mul_f32_e32 v238, v237, v236
	v_fma_f32 v239, -v235, v238, v237
	v_fmac_f32_e32 v238, v239, v236
	v_fma_f32 v235, -v235, v238, v237
	v_div_fmas_f32 v235, v235, v236, v238
	v_div_fixup_f32 v234, v235, v234, v233
	ds_write_b32 v173, v234 offset:3120
	s_waitcnt lgkmcnt(0)
; DI float bf2f(bf16_t v) { return __uint_as_float(((unsigned)v) << 16); }
; DI float siluf_(float x) { return x / (1.f + __expf(-x)); }
; DI void phase_gdn_prep(const Params& p, int l, char* smem) {
;     ...
;             for (int part = 0; part < 3; ++part) {
; #pragma unroll
;                 for (int k = 0; k < 3; ++k) { const int c = tid + 256 * k; if (c < 67 * 8) *(u32x4*)(sraw + c * 8) = raw[part * 3 + k]; }
;                 __syncthreads();
;                 const int col = part * 384 + h * 64 + ch;
;                 const float w0 = cw[col], w1 = cw[1152 + col], w2 = cw[2 * 1152 + col], w3 = cw[3 * 1152 + col];
;                 float* dst = part == 0 ? sq : (part == 1 ? sk : sv);
; #pragma unroll
;                 for (int i = 0; i < 16; ++i) {
;                     const int t = tq + 4 * i;
;                     const float x0 = bf2f(sraw[(t + 0) * 64 + ch]), x1 = bf2f(sraw[(t + 1) * 64 + ch]);
;                     const float x2 = bf2f(sraw[(t + 2) * 64 + ch]), x3 = bf2f(sraw[(t + 3) * 64 + ch]);
;                     const float a = x0 * w0 + x1 * w1 + x2 * w2 + x3 * w3;
;                     dst[t * 65 + ch] = siluf_(a);
;                 }
;                 __syncthreads();
	v_lshlrev_b32_e32 v191, 16, v191
	v_lshlrev_b32_e32 v192, 16, v192
	v_lshlrev_b32_e32 v193, 16, v193
	v_lshlrev_b32_e32 v194, 16, v194
	v_mul_f32_e32 v230, v38, v192
	v_fmac_f32_e32 v230, v37, v191
	v_fmac_f32_e32 v230, v39, v193
	v_fmac_f32_e32 v230, v54, v194
	v_lshlrev_b32_e32 v195, 16, v195
	v_lshlrev_b32_e32 v196, 16, v196
	v_lshlrev_b32_e32 v197, 16, v197
	v_lshlrev_b32_e32 v198, 16, v198
	v_mul_f32_e32 v231, v38, v196
	v_fmac_f32_e32 v231, v37, v195
	v_fmac_f32_e32 v231, v39, v197
	v_fmac_f32_e32 v231, v54, v198
	v_lshlrev_b32_e32 v199, 16, v199
	v_lshlrev_b32_e32 v200, 16, v200
	v_lshlrev_b32_e32 v201, 16, v201
	v_lshlrev_b32_e32 v202, 16, v202
	v_mul_f32_e32 v232, v38, v200
	v_fmac_f32_e32 v232, v37, v199
	v_fmac_f32_e32 v232, v39, v201
	v_fmac_f32_e32 v232, v54, v202
	v_lshlrev_b32_e32 v203, 16, v203
	v_lshlrev_b32_e32 v204, 16, v204
	v_lshlrev_b32_e32 v205, 16, v205
	v_lshlrev_b32_e32 v206, 16, v206
	v_mul_f32_e32 v233, v38, v204
	v_fmac_f32_e32 v233, v37, v203
	v_fmac_f32_e32 v233, v39, v205
	v_fmac_f32_e32 v233, v54, v206
	ds_read_u16 v191, v78 offset:54016
	ds_read_u16 v192, v78 offset:54144
	ds_read_u16 v193, v78 offset:54272
	ds_read_u16 v194, v78 offset:54400
	ds_read_u16 v195, v78 offset:54528
	ds_read_u16 v196, v78 offset:54656
	ds_read_u16 v197, v78 offset:54784
	ds_read_u16 v198, v78 offset:54912
	ds_read_u16 v199, v78 offset:55040
	ds_read_u16 v200, v78 offset:55168
	ds_read_u16 v201, v78 offset:55296
	ds_read_u16 v202, v78 offset:55424
	ds_read_u16 v203, v78 offset:55552
	ds_read_u16 v204, v78 offset:55680
	ds_read_u16 v205, v78 offset:55808
	ds_read_u16 v206, v78 offset:55936
	v_mul_f32_e32 v234, 0xbfb8aa3b, v230
	v_exp_f32_e32 v234, v234
	s_nop 0
	v_add_f32_e32 v234, 1.0, v234
	v_div_scale_f32 v235, s[4:5], v234, v234, v230
	v_rcp_f32_e32 v236, v235
	s_nop 0
	v_fma_f32 v237, -v235, v236, 1.0
	v_fmac_f32_e32 v236, v237, v236
	v_div_scale_f32 v237, vcc, v230, v234, v230
	v_mul_f32_e32 v238, v237, v236
	v_fma_f32 v239, -v235, v238, v237
	v_fmac_f32_e32 v238, v239, v236
	v_fma_f32 v235, -v235, v238, v237
	v_div_fmas_f32 v235, v235, v236, v238
	v_div_fixup_f32 v234, v235, v234, v230
	ds_write_b32 v173, v234 offset:4160
	v_mul_f32_e32 v234, 0xbfb8aa3b, v231
	v_exp_f32_e32 v234, v234
	s_nop 0
	v_add_f32_e32 v234, 1.0, v234
	v_div_scale_f32 v235, s[4:5], v234, v234, v231
	v_rcp_f32_e32 v236, v235
	s_nop 0
	v_fma_f32 v237, -v235, v236, 1.0
	v_fmac_f32_e32 v236, v237, v236
	v_div_scale_f32 v237, vcc, v231, v234, v231
	v_mul_f32_e32 v238, v237, v236
	v_fma_f32 v239, -v235, v238, v237
	v_fmac_f32_e32 v238, v239, v236
	v_fma_f32 v235, -v235, v238, v237
	v_div_fmas_f32 v235, v235, v236, v238
	v_div_fixup_f32 v234, v235, v234, v231
	ds_write_b32 v173, v234 offset:5200
	v_mul_f32_e32 v234, 0xbfb8aa3b, v232
	v_exp_f32_e32 v234, v234
	s_nop 0
	v_add_f32_e32 v234, 1.0, v234
	v_div_scale_f32 v235, s[4:5], v234, v234, v232
	v_rcp_f32_e32 v236, v235
	s_nop 0
	v_fma_f32 v237, -v235, v236, 1.0
	v_fmac_f32_e32 v236, v237, v236
	v_div_scale_f32 v237, vcc, v232, v234, v232
	v_mul_f32_e32 v238, v237, v236
	v_fma_f32 v239, -v235, v238, v237
	v_fmac_f32_e32 v238, v239, v236
	v_fma_f32 v235, -v235, v238, v237
	v_div_fmas_f32 v235, v235, v236, v238
	v_div_fixup_f32 v234, v235, v234, v232
	ds_write_b32 v173, v234 offset:6240
	v_mul_f32_e32 v234, 0xbfb8aa3b, v233
	v_exp_f32_e32 v234, v234
	s_nop 0
	v_add_f32_e32 v234, 1.0, v234
	v_div_scale_f32 v235, s[4:5], v234, v234, v233
	v_rcp_f32_e32 v236, v235
	s_nop 0
	v_fma_f32 v237, -v235, v236, 1.0
	v_fmac_f32_e32 v236, v237, v236
	v_div_scale_f32 v237, vcc, v233, v234, v233
	v_mul_f32_e32 v238, v237, v236
	v_fma_f32 v239, -v235, v238, v237
	v_fmac_f32_e32 v238, v239, v236
	v_fma_f32 v235, -v235, v238, v237
	v_div_fmas_f32 v235, v235, v236, v238
	v_div_fixup_f32 v234, v235, v234, v233
	ds_write_b32 v173, v234 offset:7280
	s_waitcnt lgkmcnt(0)
	v_lshlrev_b32_e32 v191, 16, v191
	v_lshlrev_b32_e32 v192, 16, v192
	v_lshlrev_b32_e32 v193, 16, v193
	v_lshlrev_b32_e32 v194, 16, v194
	v_mul_f32_e32 v230, v38, v192
	v_fmac_f32_e32 v230, v37, v191
	v_fmac_f32_e32 v230, v39, v193
	v_fmac_f32_e32 v230, v54, v194
	v_lshlrev_b32_e32 v195, 16, v195
	v_lshlrev_b32_e32 v196, 16, v196
	v_lshlrev_b32_e32 v197, 16, v197
	v_lshlrev_b32_e32 v198, 16, v198
	v_mul_f32_e32 v231, v38, v196
	v_fmac_f32_e32 v231, v37, v195
	v_fmac_f32_e32 v231, v39, v197
	v_fmac_f32_e32 v231, v54, v198
	v_lshlrev_b32_e32 v199, 16, v199
	v_lshlrev_b32_e32 v200, 16, v200
	v_lshlrev_b32_e32 v201, 16, v201
	v_lshlrev_b32_e32 v202, 16, v202
	v_mul_f32_e32 v232, v38, v200
	v_fmac_f32_e32 v232, v37, v199
	v_fmac_f32_e32 v232, v39, v201
	v_fmac_f32_e32 v232, v54, v202
	v_lshlrev_b32_e32 v203, 16, v203
	v_lshlrev_b32_e32 v204, 16, v204
	v_lshlrev_b32_e32 v205, 16, v205
	v_lshlrev_b32_e32 v206, 16, v206
	v_mul_f32_e32 v233, v38, v204
	v_fmac_f32_e32 v233, v37, v203
	v_fmac_f32_e32 v233, v39, v205
	v_fmac_f32_e32 v233, v54, v206
	ds_read_u16 v191, v78 offset:56064
	ds_read_u16 v192, v78 offset:56192
	ds_read_u16 v193, v78 offset:56320
	ds_read_u16 v194, v78 offset:56448
	ds_read_u16 v195, v78 offset:56576
	ds_read_u16 v196, v78 offset:56704
	ds_read_u16 v197, v78 offset:56832
	ds_read_u16 v198, v78 offset:56960
	ds_read_u16 v199, v78 offset:57088
	ds_read_u16 v200, v78 offset:57216
	ds_read_u16 v201, v78 offset:57344
	ds_read_u16 v202, v78 offset:57472
	ds_read_u16 v203, v78 offset:57600
	ds_read_u16 v204, v78 offset:57728
	ds_read_u16 v205, v78 offset:57856
	ds_read_u16 v206, v78 offset:57984
	v_mul_f32_e32 v234, 0xbfb8aa3b, v230
	v_exp_f32_e32 v234, v234
	s_nop 0
	v_add_f32_e32 v234, 1.0, v234
; DI float bf2f(bf16_t v) { return __uint_as_float(((unsigned)v) << 16); }
; DI float siluf_(float x) { return x / (1.f + __expf(-x)); }
; DI void phase_gdn_prep(const Params& p, int l, char* smem) {
;     ...
;             for (int part = 0; part < 3; ++part) {
; #pragma unroll
;                 for (int k = 0; k < 3; ++k) { const int c = tid + 256 * k; if (c < 67 * 8) *(u32x4*)(sraw + c * 8) = raw[part * 3 + k]; }
;                 __syncthreads();
;                 const int col = part * 384 + h * 64 + ch;
;                 const float w0 = cw[col], w1 = cw[1152 + col], w2 = cw[2 * 1152 + col], w3 = cw[3 * 1152 + col];
;                 float* dst = part == 0 ? sq : (part == 1 ? sk : sv);
; #pragma unroll
;                 for (int i = 0; i < 16; ++i) {
;                     const int t = tq + 4 * i;
;                     const float x0 = bf2f(sraw[(t + 0) * 64 + ch]), x1 = bf2f(sraw[(t + 1) * 64 + ch]);
;                     const float x2 = bf2f(sraw[(t + 2) * 64 + ch]), x3 = bf2f(sraw[(t + 3) * 64 + ch]);
;                     const float a = x0 * w0 + x1 * w1 + x2 * w2 + x3 * w3;
;                     dst[t * 65 + ch] = siluf_(a);
;                 }
;                 __syncthreads();
	v_div_scale_f32 v235, s[4:5], v234, v234, v230
	v_rcp_f32_e32 v236, v235
	s_nop 0
	v_fma_f32 v237, -v235, v236, 1.0
	v_fmac_f32_e32 v236, v237, v236
	v_div_scale_f32 v237, vcc, v230, v234, v230
	v_mul_f32_e32 v238, v237, v236
	v_fma_f32 v239, -v235, v238, v237
	v_fmac_f32_e32 v238, v239, v236
	v_fma_f32 v235, -v235, v238, v237
	v_div_fmas_f32 v235, v235, v236, v238
	v_div_fixup_f32 v234, v235, v234, v230
	ds_write_b32 v173, v234 offset:8320
	v_mul_f32_e32 v234, 0xbfb8aa3b, v231
	v_exp_f32_e32 v234, v234
	s_nop 0
	v_add_f32_e32 v234, 1.0, v234
	v_div_scale_f32 v235, s[4:5], v234, v234, v231
	v_rcp_f32_e32 v236, v235
	s_nop 0
	v_fma_f32 v237, -v235, v236, 1.0
	v_fmac_f32_e32 v236, v237, v236
	v_div_scale_f32 v237, vcc, v231, v234, v231
	v_mul_f32_e32 v238, v237, v236
	v_fma_f32 v239, -v235, v238, v237
	v_fmac_f32_e32 v238, v239, v236
	v_fma_f32 v235, -v235, v238, v237
	v_div_fmas_f32 v235, v235, v236, v238
	v_div_fixup_f32 v234, v235, v234, v231
	ds_write_b32 v173, v234 offset:9360
	v_mul_f32_e32 v234, 0xbfb8aa3b, v232
	v_exp_f32_e32 v234, v234
	s_nop 0
	v_add_f32_e32 v234, 1.0, v234
	v_div_scale_f32 v235, s[4:5], v234, v234, v232
	v_rcp_f32_e32 v236, v235
	s_nop 0
	v_fma_f32 v237, -v235, v236, 1.0
	v_fmac_f32_e32 v236, v237, v236
	v_div_scale_f32 v237, vcc, v232, v234, v232
	v_mul_f32_e32 v238, v237, v236
	v_fma_f32 v239, -v235, v238, v237
	v_fmac_f32_e32 v238, v239, v236
	v_fma_f32 v235, -v235, v238, v237
	v_div_fmas_f32 v235, v235, v236, v238
	v_div_fixup_f32 v234, v235, v234, v232
	ds_write_b32 v173, v234 offset:10400
	v_mul_f32_e32 v234, 0xbfb8aa3b, v233
	v_exp_f32_e32 v234, v234
	s_nop 0
	v_add_f32_e32 v234, 1.0, v234
	v_div_scale_f32 v235, s[4:5], v234, v234, v233
	v_rcp_f32_e32 v236, v235
	s_nop 0
	v_fma_f32 v237, -v235, v236, 1.0
	v_fmac_f32_e32 v236, v237, v236
	v_div_scale_f32 v237, vcc, v233, v234, v233
	v_mul_f32_e32 v238, v237, v236
	v_fma_f32 v239, -v235, v238, v237
	v_fmac_f32_e32 v238, v239, v236
	v_fma_f32 v235, -v235, v238, v237
	v_div_fmas_f32 v235, v235, v236, v238
	v_div_fixup_f32 v234, v235, v234, v233
	ds_write_b32 v173, v234 offset:11440
	s_waitcnt lgkmcnt(0)
	v_lshlrev_b32_e32 v191, 16, v191
	v_lshlrev_b32_e32 v192, 16, v192
	v_lshlrev_b32_e32 v193, 16, v193
	v_lshlrev_b32_e32 v194, 16, v194
	v_mul_f32_e32 v230, v38, v192
	v_fmac_f32_e32 v230, v37, v191
	v_fmac_f32_e32 v230, v39, v193
	v_fmac_f32_e32 v230, v54, v194
	v_lshlrev_b32_e32 v195, 16, v195
	v_lshlrev_b32_e32 v196, 16, v196
	v_lshlrev_b32_e32 v197, 16, v197
	v_lshlrev_b32_e32 v198, 16, v198
	v_mul_f32_e32 v231, v38, v196
	v_fmac_f32_e32 v231, v37, v195
	v_fmac_f32_e32 v231, v39, v197
	v_fmac_f32_e32 v231, v54, v198
	v_lshlrev_b32_e32 v199, 16, v199
	v_lshlrev_b32_e32 v200, 16, v200
	v_lshlrev_b32_e32 v201, 16, v201
	v_lshlrev_b32_e32 v202, 16, v202
	v_mul_f32_e32 v232, v38, v200
	v_fmac_f32_e32 v232, v37, v199
	v_fmac_f32_e32 v232, v39, v201
	v_fmac_f32_e32 v232, v54, v202
	v_lshlrev_b32_e32 v203, 16, v203
	v_lshlrev_b32_e32 v204, 16, v204
	v_lshlrev_b32_e32 v205, 16, v205
	v_lshlrev_b32_e32 v206, 16, v206
	v_mul_f32_e32 v233, v38, v204
	v_fmac_f32_e32 v233, v37, v203
	v_fmac_f32_e32 v233, v39, v205
	v_fmac_f32_e32 v233, v54, v206
	v_mul_f32_e32 v234, 0xbfb8aa3b, v230
	v_exp_f32_e32 v234, v234
	s_nop 0
	v_add_f32_e32 v234, 1.0, v234
	v_div_scale_f32 v235, s[4:5], v234, v234, v230
	v_rcp_f32_e32 v236, v235
	s_nop 0
	v_fma_f32 v237, -v235, v236, 1.0
	v_fmac_f32_e32 v236, v237, v236
	v_div_scale_f32 v237, vcc, v230, v234, v230
	v_mul_f32_e32 v238, v237, v236
	v_fma_f32 v239, -v235, v238, v237
	v_fmac_f32_e32 v238, v239, v236
	v_fma_f32 v235, -v235, v238, v237
	v_div_fmas_f32 v235, v235, v236, v238
	v_div_fixup_f32 v234, v235, v234, v230
	ds_write_b32 v173, v234 offset:12480
	v_mul_f32_e32 v234, 0xbfb8aa3b, v231
	v_exp_f32_e32 v234, v234
	s_nop 0
	v_add_f32_e32 v234, 1.0, v234
	v_div_scale_f32 v235, s[4:5], v234, v234, v231
	v_rcp_f32_e32 v236, v235
	s_nop 0
	v_fma_f32 v237, -v235, v236, 1.0
	v_fmac_f32_e32 v236, v237, v236
	v_div_scale_f32 v237, vcc, v231, v234, v231
	v_mul_f32_e32 v238, v237, v236
	v_fma_f32 v239, -v235, v238, v237
	v_fmac_f32_e32 v238, v239, v236
	v_fma_f32 v235, -v235, v238, v237
	v_div_fmas_f32 v235, v235, v236, v238
	v_div_fixup_f32 v234, v235, v234, v231
	ds_write_b32 v173, v234 offset:13520
	v_mul_f32_e32 v234, 0xbfb8aa3b, v232
	v_exp_f32_e32 v234, v234
	s_nop 0
	v_add_f32_e32 v234, 1.0, v234
	v_div_scale_f32 v235, s[4:5], v234, v234, v232
	v_rcp_f32_e32 v236, v235
	s_nop 0
	v_fma_f32 v237, -v235, v236, 1.0
	v_fmac_f32_e32 v236, v237, v236
	v_div_scale_f32 v237, vcc, v232, v234, v232
	v_mul_f32_e32 v238, v237, v236
	v_fma_f32 v239, -v235, v238, v237
	v_fmac_f32_e32 v238, v239, v236
	v_fma_f32 v235, -v235, v238, v237
	v_div_fmas_f32 v235, v235, v236, v238
	v_div_fixup_f32 v234, v235, v234, v232
	ds_write_b32 v173, v234 offset:14560
	v_mul_f32_e32 v234, 0xbfb8aa3b, v233
	v_exp_f32_e32 v234, v234
	s_nop 0
	v_add_f32_e32 v234, 1.0, v234
	v_div_scale_f32 v235, s[4:5], v234, v234, v233
	v_rcp_f32_e32 v236, v235
	s_nop 0
	v_fma_f32 v237, -v235, v236, 1.0
	v_fmac_f32_e32 v236, v237, v236
	v_div_scale_f32 v237, vcc, v233, v234, v233
	v_mul_f32_e32 v238, v237, v236
	v_fma_f32 v239, -v235, v238, v237
	v_fmac_f32_e32 v238, v239, v236
	v_fma_f32 v235, -v235, v238, v237
	v_div_fmas_f32 v235, v235, v236, v238
	v_div_fixup_f32 v234, v235, v234, v233
	ds_write_b32 v173, v234 offset:15600
	s_waitcnt lgkmcnt(0)
	s_barrier
	s_and_saveexec_b64 s[4:5], s[42:43]
	s_cbranch_execnz .LBB0_343
	s_or_b64 exec, exec, s[4:5]
	s_and_saveexec_b64 s[4:5], s[44:45]
	s_cbranch_execnz .LBB0_344

; DI float bf2f(bf16_t v) { return __uint_as_float(((unsigned)v) << 16); }
; DI float siluf_(float x) { return x / (1.f + __expf(-x)); }
; DI void phase_gdn_prep(const Params& p, int l, char* smem) {
;     ...
;             for (int part = 0; part < 3; ++part) {
; #pragma unroll
;                 for (int k = 0; k < 3; ++k) { const int c = tid + 256 * k; if (c < 67 * 8) *(u32x4*)(sraw + c * 8) = raw[part * 3 + k]; }
;                 __syncthreads();
;                 const int col = part * 384 + h * 64 + ch;
;                 const float w0 = cw[col], w1 = cw[1152 + col], w2 = cw[2 * 1152 + col], w3 = cw[3 * 1152 + col];
;                 float* dst = part == 0 ? sq : (part == 1 ? sk : sv);
; #pragma unroll
;                 for (int i = 0; i < 16; ++i) {
;                     const int t = tq + 4 * i;
;                     const float x0 = bf2f(sraw[(t + 0) * 64 + ch]), x1 = bf2f(sraw[(t + 1) * 64 + ch]);
;                     const float x2 = bf2f(sraw[(t + 2) * 64 + ch]), x3 = bf2f(sraw[(t + 3) * 64 + ch]);
;                     const float a = x0 * w0 + x1 * w1 + x2 * w2 + x3 * w3;
;                     dst[t * 65 + ch] = siluf_(a);
;                 }
;                 __syncthreads();
.LBB0_276:
	s_or_b64 exec, exec, s[4:5]
	v_add_co_u32_e32 v2, vcc, 0x1000, v24
	s_waitcnt lgkmcnt(0)
	s_nop 0
	v_addc_co_u32_e32 v3, vcc, 0, v25, vcc
	s_barrier
	s_ashr_i32 s87, s86, 31
	ds_read_u16 v191, v78 offset:49920
	ds_read_u16 v192, v78 offset:50048
	ds_read_u16 v193, v78 offset:50176
	ds_read_u16 v194, v78 offset:50304
	ds_read_u16 v195, v78 offset:50432
	ds_read_u16 v196, v78 offset:50560
	ds_read_u16 v197, v78 offset:50688
	ds_read_u16 v198, v78 offset:50816
	ds_read_u16 v199, v78 offset:50944
	ds_read_u16 v200, v78 offset:51072
	ds_read_u16 v201, v78 offset:51200
	ds_read_u16 v202, v78 offset:51328
	ds_read_u16 v203, v78 offset:51456
	ds_read_u16 v204, v78 offset:51584
	ds_read_u16 v205, v78 offset:51712
	ds_read_u16 v206, v78 offset:51840
	s_waitcnt lgkmcnt(0)
	v_lshlrev_b32_e32 v191, 16, v191
	v_lshlrev_b32_e32 v192, 16, v192
	v_lshlrev_b32_e32 v193, 16, v193
	v_lshlrev_b32_e32 v194, 16, v194
	v_mul_f32_e32 v230, v185, v192
	v_fmac_f32_e32 v230, v76, v191
	v_fmac_f32_e32 v230, v186, v193
	v_fmac_f32_e32 v230, v187, v194
	v_lshlrev_b32_e32 v195, 16, v195
	v_lshlrev_b32_e32 v196, 16, v196
	v_lshlrev_b32_e32 v197, 16, v197
	v_lshlrev_b32_e32 v198, 16, v198
	v_mul_f32_e32 v231, v185, v196
	v_fmac_f32_e32 v231, v76, v195
	v_fmac_f32_e32 v231, v186, v197
	v_fmac_f32_e32 v231, v187, v198
	v_lshlrev_b32_e32 v199, 16, v199
	v_lshlrev_b32_e32 v200, 16, v200
	v_lshlrev_b32_e32 v201, 16, v201
	v_lshlrev_b32_e32 v202, 16, v202
	v_mul_f32_e32 v232, v185, v200
	v_fmac_f32_e32 v232, v76, v199
	v_fmac_f32_e32 v232, v186, v201
	v_fmac_f32_e32 v232, v187, v202
	v_lshlrev_b32_e32 v203, 16, v203
	v_lshlrev_b32_e32 v204, 16, v204
	v_lshlrev_b32_e32 v205, 16, v205
	v_lshlrev_b32_e32 v206, 16, v206
	v_mul_f32_e32 v233, v185, v204
	v_fmac_f32_e32 v233, v76, v203
	v_fmac_f32_e32 v233, v186, v205
	v_fmac_f32_e32 v233, v187, v206
	ds_read_u16 v191, v78 offset:51968
	ds_read_u16 v192, v78 offset:52096
	ds_read_u16 v193, v78 offset:52224
	ds_read_u16 v194, v78 offset:52352
	ds_read_u16 v195, v78 offset:52480
	ds_read_u16 v196, v78 offset:52608
	ds_read_u16 v197, v78 offset:52736
	ds_read_u16 v198, v78 offset:52864
	ds_read_u16 v199, v78 offset:52992
	ds_read_u16 v200, v78 offset:53120
	ds_read_u16 v201, v78 offset:53248
	ds_read_u16 v202, v78 offset:53376
	ds_read_u16 v203, v78 offset:53504
	ds_read_u16 v204, v78 offset:53632
	ds_read_u16 v205, v78 offset:53760
	ds_read_u16 v206, v78 offset:53888
	v_mul_f32_e32 v234, 0xbfb8aa3b, v230
	v_exp_f32_e32 v234, v234
	s_nop 0
	v_add_f32_e32 v234, 1.0, v234
	v_div_scale_f32 v235, s[4:5], v234, v234, v230
	v_rcp_f32_e32 v236, v235
	s_nop 0
	v_fma_f32 v237, -v235, v236, 1.0
	v_fmac_f32_e32 v236, v237, v236
	v_div_scale_f32 v237, vcc, v230, v234, v230
	v_mul_f32_e32 v238, v237, v236
	v_fma_f32 v239, -v235, v238, v237
	v_fmac_f32_e32 v238, v239, v236
	v_fma_f32 v235, -v235, v238, v237
	v_div_fmas_f32 v235, v235, v236, v238
	v_div_fixup_f32 v234, v235, v234, v230
	ds_write_b32 v173, v234 offset:33280
	v_mul_f32_e32 v234, 0xbfb8aa3b, v231
	v_exp_f32_e32 v234, v234
	s_nop 0
	v_add_f32_e32 v234, 1.0, v234
	v_div_scale_f32 v235, s[4:5], v234, v234, v231
	v_rcp_f32_e32 v236, v235
	s_nop 0
	v_fma_f32 v237, -v235, v236, 1.0
	v_fmac_f32_e32 v236, v237, v236
	v_div_scale_f32 v237, vcc, v231, v234, v231
	v_mul_f32_e32 v238, v237, v236
	v_fma_f32 v239, -v235, v238, v237
	v_fmac_f32_e32 v238, v239, v236
	v_fma_f32 v235, -v235, v238, v237
	v_div_fmas_f32 v235, v235, v236, v238
	v_div_fixup_f32 v234, v235, v234, v231
	ds_write_b32 v173, v234 offset:34320
	v_mul_f32_e32 v234, 0xbfb8aa3b, v232
	v_exp_f32_e32 v234, v234
	s_nop 0
	v_add_f32_e32 v234, 1.0, v234
	v_div_scale_f32 v235, s[4:5], v234, v234, v232
	v_rcp_f32_e32 v236, v235
	s_nop 0
	v_fma_f32 v237, -v235, v236, 1.0
	v_fmac_f32_e32 v236, v237, v236
	v_div_scale_f32 v237, vcc, v232, v234, v232
	v_mul_f32_e32 v238, v237, v236
	v_fma_f32 v239, -v235, v238, v237
	v_fmac_f32_e32 v238, v239, v236
	v_fma_f32 v235, -v235, v238, v237
	v_div_fmas_f32 v235, v235, v236, v238
	v_div_fixup_f32 v234, v235, v234, v232
	ds_write_b32 v173, v234 offset:35360
	v_mul_f32_e32 v234, 0xbfb8aa3b, v233
	v_exp_f32_e32 v234, v234
	s_nop 0
	v_add_f32_e32 v234, 1.0, v234
	v_div_scale_f32 v235, s[4:5], v234, v234, v233
	v_rcp_f32_e32 v236, v235
	s_nop 0
	v_fma_f32 v237, -v235, v236, 1.0
	v_fmac_f32_e32 v236, v237, v236
	v_div_scale_f32 v237, vcc, v233, v234, v233
	v_mul_f32_e32 v238, v237, v236
	v_fma_f32 v239, -v235, v238, v237
	v_fmac_f32_e32 v238, v239, v236
	v_fma_f32 v235, -v235, v238, v237
	v_div_fmas_f32 v235, v235, v236, v238
	v_div_fixup_f32 v234, v235, v234, v233
	ds_write_b32 v173, v234 offset:36400
	s_waitcnt lgkmcnt(0)
; DI float bf2f(bf16_t v) { return __uint_as_float(((unsigned)v) << 16); }
; DI float siluf_(float x) { return x / (1.f + __expf(-x)); }
; DI void phase_gdn_prep(const Params& p, int l, char* smem) {
;     ...
;             for (int part = 0; part < 3; ++part) {
; #pragma unroll
;                 for (int k = 0; k < 3; ++k) { const int c = tid + 256 * k; if (c < 67 * 8) *(u32x4*)(sraw + c * 8) = raw[part * 3 + k]; }
;                 __syncthreads();
;                 const int col = part * 384 + h * 64 + ch;
;                 const float w0 = cw[col], w1 = cw[1152 + col], w2 = cw[2 * 1152 + col], w3 = cw[3 * 1152 + col];
;                 float* dst = part == 0 ? sq : (part == 1 ? sk : sv);
; #pragma unroll
;                 for (int i = 0; i < 16; ++i) {
;                     const int t = tq + 4 * i;
;                     const float x0 = bf2f(sraw[(t + 0) * 64 + ch]), x1 = bf2f(sraw[(t + 1) * 64 + ch]);
;                     const float x2 = bf2f(sraw[(t + 2) * 64 + ch]), x3 = bf2f(sraw[(t + 3) * 64 + ch]);
;                     const float a = x0 * w0 + x1 * w1 + x2 * w2 + x3 * w3;
;                     dst[t * 65 + ch] = siluf_(a);
;                 }
;                 __syncthreads();
	v_lshlrev_b32_e32 v191, 16, v191
	v_lshlrev_b32_e32 v192, 16, v192
	v_lshlrev_b32_e32 v193, 16, v193
	v_lshlrev_b32_e32 v194, 16, v194
	v_mul_f32_e32 v230, v185, v192
	v_fmac_f32_e32 v230, v76, v191
	v_fmac_f32_e32 v230, v186, v193
	v_fmac_f32_e32 v230, v187, v194
	v_lshlrev_b32_e32 v195, 16, v195
	v_lshlrev_b32_e32 v196, 16, v196
	v_lshlrev_b32_e32 v197, 16, v197
	v_lshlrev_b32_e32 v198, 16, v198
	v_mul_f32_e32 v231, v185, v196
	v_fmac_f32_e32 v231, v76, v195
	v_fmac_f32_e32 v231, v186, v197
	v_fmac_f32_e32 v231, v187, v198
	v_lshlrev_b32_e32 v199, 16, v199
	v_lshlrev_b32_e32 v200, 16, v200
	v_lshlrev_b32_e32 v201, 16, v201
	v_lshlrev_b32_e32 v202, 16, v202
	v_mul_f32_e32 v232, v185, v200
	v_fmac_f32_e32 v232, v76, v199
	v_fmac_f32_e32 v232, v186, v201
	v_fmac_f32_e32 v232, v187, v202
	v_lshlrev_b32_e32 v203, 16, v203
	v_lshlrev_b32_e32 v204, 16, v204
	v_lshlrev_b32_e32 v205, 16, v205
	v_lshlrev_b32_e32 v206, 16, v206
	v_mul_f32_e32 v233, v185, v204
	v_fmac_f32_e32 v233, v76, v203
	v_fmac_f32_e32 v233, v186, v205
	v_fmac_f32_e32 v233, v187, v206
	ds_read_u16 v191, v78 offset:54016
	ds_read_u16 v192, v78 offset:54144
	ds_read_u16 v193, v78 offset:54272
	ds_read_u16 v194, v78 offset:54400
	ds_read_u16 v195, v78 offset:54528
	ds_read_u16 v196, v78 offset:54656
	ds_read_u16 v197, v78 offset:54784
	ds_read_u16 v198, v78 offset:54912
	ds_read_u16 v199, v78 offset:55040
	ds_read_u16 v200, v78 offset:55168
	ds_read_u16 v201, v78 offset:55296
	ds_read_u16 v202, v78 offset:55424
	ds_read_u16 v203, v78 offset:55552
	ds_read_u16 v204, v78 offset:55680
	ds_read_u16 v205, v78 offset:55808
	ds_read_u16 v206, v78 offset:55936
	v_mul_f32_e32 v234, 0xbfb8aa3b, v230
	v_exp_f32_e32 v234, v234
	s_nop 0
	v_add_f32_e32 v234, 1.0, v234
	v_div_scale_f32 v235, s[4:5], v234, v234, v230
	v_rcp_f32_e32 v236, v235
	s_nop 0
	v_fma_f32 v237, -v235, v236, 1.0
	v_fmac_f32_e32 v236, v237, v236
	v_div_scale_f32 v237, vcc, v230, v234, v230
	v_mul_f32_e32 v238, v237, v236
	v_fma_f32 v239, -v235, v238, v237
	v_fmac_f32_e32 v238, v239, v236
	v_fma_f32 v235, -v235, v238, v237
	v_div_fmas_f32 v235, v235, v236, v238
	v_div_fixup_f32 v234, v235, v234, v230
	ds_write_b32 v173, v234 offset:37440
	v_mul_f32_e32 v234, 0xbfb8aa3b, v231
	v_exp_f32_e32 v234, v234
	s_nop 0
	v_add_f32_e32 v234, 1.0, v234
	v_div_scale_f32 v235, s[4:5], v234, v234, v231
	v_rcp_f32_e32 v236, v235
	s_nop 0
	v_fma_f32 v237, -v235, v236, 1.0
	v_fmac_f32_e32 v236, v237, v236
	v_div_scale_f32 v237, vcc, v231, v234, v231
	v_mul_f32_e32 v238, v237, v236
	v_fma_f32 v239, -v235, v238, v237
	v_fmac_f32_e32 v238, v239, v236
	v_fma_f32 v235, -v235, v238, v237
	v_div_fmas_f32 v235, v235, v236, v238
	v_div_fixup_f32 v234, v235, v234, v231
	ds_write_b32 v173, v234 offset:38480
	v_mul_f32_e32 v234, 0xbfb8aa3b, v232
	v_exp_f32_e32 v234, v234
	s_nop 0
	v_add_f32_e32 v234, 1.0, v234
	v_div_scale_f32 v235, s[4:5], v234, v234, v232
	v_rcp_f32_e32 v236, v235
	s_nop 0
	v_fma_f32 v237, -v235, v236, 1.0
	v_fmac_f32_e32 v236, v237, v236
	v_div_scale_f32 v237, vcc, v232, v234, v232
	v_mul_f32_e32 v238, v237, v236
	v_fma_f32 v239, -v235, v238, v237
	v_fmac_f32_e32 v238, v239, v236
	v_fma_f32 v235, -v235, v238, v237
	v_div_fmas_f32 v235, v235, v236, v238
	v_div_fixup_f32 v234, v235, v234, v232
	ds_write_b32 v173, v234 offset:39520
	v_mul_f32_e32 v234, 0xbfb8aa3b, v233
	v_exp_f32_e32 v234, v234
	s_nop 0
	v_add_f32_e32 v234, 1.0, v234
	v_div_scale_f32 v235, s[4:5], v234, v234, v233
	v_rcp_f32_e32 v236, v235
	s_nop 0
	v_fma_f32 v237, -v235, v236, 1.0
	v_fmac_f32_e32 v236, v237, v236
	v_div_scale_f32 v237, vcc, v233, v234, v233
	v_mul_f32_e32 v238, v237, v236
	v_fma_f32 v239, -v235, v238, v237
	v_fmac_f32_e32 v238, v239, v236
	v_fma_f32 v235, -v235, v238, v237
	v_div_fmas_f32 v235, v235, v236, v238
	v_div_fixup_f32 v234, v235, v234, v233
	ds_write_b32 v173, v234 offset:40560
	s_waitcnt lgkmcnt(0)
	v_lshlrev_b32_e32 v191, 16, v191
	v_lshlrev_b32_e32 v192, 16, v192
	v_lshlrev_b32_e32 v193, 16, v193
	v_lshlrev_b32_e32 v194, 16, v194
	v_mul_f32_e32 v230, v185, v192
	v_fmac_f32_e32 v230, v76, v191
	v_fmac_f32_e32 v230, v186, v193
	v_fmac_f32_e32 v230, v187, v194
	v_lshlrev_b32_e32 v195, 16, v195
	v_lshlrev_b32_e32 v196, 16, v196
	v_lshlrev_b32_e32 v197, 16, v197
	v_lshlrev_b32_e32 v198, 16, v198
	v_mul_f32_e32 v231, v185, v196
	v_fmac_f32_e32 v231, v76, v195
	v_fmac_f32_e32 v231, v186, v197
	v_fmac_f32_e32 v231, v187, v198
	v_lshlrev_b32_e32 v199, 16, v199
	v_lshlrev_b32_e32 v200, 16, v200
	v_lshlrev_b32_e32 v201, 16, v201
	v_lshlrev_b32_e32 v202, 16, v202
	v_mul_f32_e32 v232, v185, v200
	v_fmac_f32_e32 v232, v76, v199
	v_fmac_f32_e32 v232, v186, v201
	v_fmac_f32_e32 v232, v187, v202
	v_lshlrev_b32_e32 v203, 16, v203
	v_lshlrev_b32_e32 v204, 16, v204
	v_lshlrev_b32_e32 v205, 16, v205
	v_lshlrev_b32_e32 v206, 16, v206
	v_mul_f32_e32 v233, v185, v204
	v_fmac_f32_e32 v233, v76, v203
	v_fmac_f32_e32 v233, v186, v205
	v_fmac_f32_e32 v233, v187, v206
	ds_read_u16 v191, v78 offset:56064
	ds_read_u16 v192, v78 offset:56192
	ds_read_u16 v193, v78 offset:56320
	ds_read_u16 v194, v78 offset:56448
	ds_read_u16 v195, v78 offset:56576
	ds_read_u16 v196, v78 offset:56704
	ds_read_u16 v197, v78 offset:56832
	ds_read_u16 v198, v78 offset:56960
	ds_read_u16 v199, v78 offset:57088
	ds_read_u16 v200, v78 offset:57216
	ds_read_u16 v201, v78 offset:57344
	ds_read_u16 v202, v78 offset:57472
	ds_read_u16 v203, v78 offset:57600
	ds_read_u16 v204, v78 offset:57728
	ds_read_u16 v205, v78 offset:57856
	ds_read_u16 v206, v78 offset:57984
	v_mul_f32_e32 v234, 0xbfb8aa3b, v230
	v_exp_f32_e32 v234, v234
	s_nop 0
	v_add_f32_e32 v234, 1.0, v234
	v_div_scale_f32 v235, s[4:5], v234, v234, v230
; DI float bf2f(bf16_t v) { return __uint_as_float(((unsigned)v) << 16); }
; DI float siluf_(float x) { return x / (1.f + __expf(-x)); }
; DI void phase_gdn_prep(const Params& p, int l, char* smem) {
;     ...
;             for (int part = 0; part < 3; ++part) {
; #pragma unroll
;                 for (int k = 0; k < 3; ++k) { const int c = tid + 256 * k; if (c < 67 * 8) *(u32x4*)(sraw + c * 8) = raw[part * 3 + k]; }
;                 __syncthreads();
;                 const int col = part * 384 + h * 64 + ch;
;                 const float w0 = cw[col], w1 = cw[1152 + col], w2 = cw[2 * 1152 + col], w3 = cw[3 * 1152 + col];
;                 float* dst = part == 0 ? sq : (part == 1 ? sk : sv);
; #pragma unroll
;                 for (int i = 0; i < 16; ++i) {
;                     const int t = tq + 4 * i;
;                     const float x0 = bf2f(sraw[(t + 0) * 64 + ch]), x1 = bf2f(sraw[(t + 1) * 64 + ch]);
;                     const float x2 = bf2f(sraw[(t + 2) * 64 + ch]), x3 = bf2f(sraw[(t + 3) * 64 + ch]);
;                     const float a = x0 * w0 + x1 * w1 + x2 * w2 + x3 * w3;
;                     dst[t * 65 + ch] = siluf_(a);
;                 }
;                 __syncthreads();
;             }
;         }
;         const float bb = pbb, aa = paa;
;         if (tid < 64) {
	v_rcp_f32_e32 v236, v235
	s_nop 0
	v_fma_f32 v237, -v235, v236, 1.0
	v_fmac_f32_e32 v236, v237, v236
	v_div_scale_f32 v237, vcc, v230, v234, v230
	v_mul_f32_e32 v238, v237, v236
	v_fma_f32 v239, -v235, v238, v237
	v_fmac_f32_e32 v238, v239, v236
	v_fma_f32 v235, -v235, v238, v237
	v_div_fmas_f32 v235, v235, v236, v238
	v_div_fixup_f32 v234, v235, v234, v230
	ds_write_b32 v173, v234 offset:41600
	v_mul_f32_e32 v234, 0xbfb8aa3b, v231
	v_exp_f32_e32 v234, v234
	s_nop 0
	v_add_f32_e32 v234, 1.0, v234
	v_div_scale_f32 v235, s[4:5], v234, v234, v231
	v_rcp_f32_e32 v236, v235
	s_nop 0
	v_fma_f32 v237, -v235, v236, 1.0
	v_fmac_f32_e32 v236, v237, v236
	v_div_scale_f32 v237, vcc, v231, v234, v231
	v_mul_f32_e32 v238, v237, v236
	v_fma_f32 v239, -v235, v238, v237
	v_fmac_f32_e32 v238, v239, v236
	v_fma_f32 v235, -v235, v238, v237
	v_div_fmas_f32 v235, v235, v236, v238
	v_div_fixup_f32 v234, v235, v234, v231
	ds_write_b32 v173, v234 offset:42640
	v_mul_f32_e32 v234, 0xbfb8aa3b, v232
	v_exp_f32_e32 v234, v234
	s_nop 0
	v_add_f32_e32 v234, 1.0, v234
	v_div_scale_f32 v235, s[4:5], v234, v234, v232
	v_rcp_f32_e32 v236, v235
	s_nop 0
	v_fma_f32 v237, -v235, v236, 1.0
	v_fmac_f32_e32 v236, v237, v236
	v_div_scale_f32 v237, vcc, v232, v234, v232
	v_mul_f32_e32 v238, v237, v236
	v_fma_f32 v239, -v235, v238, v237
	v_fmac_f32_e32 v238, v239, v236
	v_fma_f32 v235, -v235, v238, v237
	v_div_fmas_f32 v235, v235, v236, v238
	v_div_fixup_f32 v234, v235, v234, v232
	ds_write_b32 v173, v234 offset:43680
	v_mul_f32_e32 v234, 0xbfb8aa3b, v233
	v_exp_f32_e32 v234, v234
	s_nop 0
	v_add_f32_e32 v234, 1.0, v234
	v_div_scale_f32 v235, s[4:5], v234, v234, v233
	v_rcp_f32_e32 v236, v235
	s_nop 0
	v_fma_f32 v237, -v235, v236, 1.0
	v_fmac_f32_e32 v236, v237, v236
	v_div_scale_f32 v237, vcc, v233, v234, v233
	v_mul_f32_e32 v238, v237, v236
	v_fma_f32 v239, -v235, v238, v237
	v_fmac_f32_e32 v238, v239, v236
	v_fma_f32 v235, -v235, v238, v237
	v_div_fmas_f32 v235, v235, v236, v238
	v_div_fixup_f32 v234, v235, v234, v233
	ds_write_b32 v173, v234 offset:44720
	s_waitcnt lgkmcnt(0)
	v_lshlrev_b32_e32 v191, 16, v191
	v_lshlrev_b32_e32 v192, 16, v192
	v_lshlrev_b32_e32 v193, 16, v193
	v_lshlrev_b32_e32 v194, 16, v194
	v_mul_f32_e32 v230, v185, v192
	v_fmac_f32_e32 v230, v76, v191
	v_fmac_f32_e32 v230, v186, v193
	v_fmac_f32_e32 v230, v187, v194
	v_lshlrev_b32_e32 v195, 16, v195
	v_lshlrev_b32_e32 v196, 16, v196
	v_lshlrev_b32_e32 v197, 16, v197
	v_lshlrev_b32_e32 v198, 16, v198
	v_mul_f32_e32 v231, v185, v196
	v_fmac_f32_e32 v231, v76, v195
	v_fmac_f32_e32 v231, v186, v197
	v_fmac_f32_e32 v231, v187, v198
	v_lshlrev_b32_e32 v199, 16, v199
	v_lshlrev_b32_e32 v200, 16, v200
	v_lshlrev_b32_e32 v201, 16, v201
	v_lshlrev_b32_e32 v202, 16, v202
	v_mul_f32_e32 v232, v185, v200
	v_fmac_f32_e32 v232, v76, v199
	v_fmac_f32_e32 v232, v186, v201
	v_fmac_f32_e32 v232, v187, v202
	v_lshlrev_b32_e32 v203, 16, v203
	v_lshlrev_b32_e32 v204, 16, v204
	v_lshlrev_b32_e32 v205, 16, v205
	v_lshlrev_b32_e32 v206, 16, v206
	v_mul_f32_e32 v233, v185, v204
	v_fmac_f32_e32 v233, v76, v203
	v_fmac_f32_e32 v233, v186, v205
	v_fmac_f32_e32 v233, v187, v206
	v_mul_f32_e32 v234, 0xbfb8aa3b, v230
	v_exp_f32_e32 v234, v234
	s_nop 0
	v_add_f32_e32 v234, 1.0, v234
	v_div_scale_f32 v235, s[4:5], v234, v234, v230
	v_rcp_f32_e32 v236, v235
	s_nop 0
	v_fma_f32 v237, -v235, v236, 1.0
	v_fmac_f32_e32 v236, v237, v236
	v_div_scale_f32 v237, vcc, v230, v234, v230
	v_mul_f32_e32 v238, v237, v236
	v_fma_f32 v239, -v235, v238, v237
	v_fmac_f32_e32 v238, v239, v236
	v_fma_f32 v235, -v235, v238, v237
	v_div_fmas_f32 v235, v235, v236, v238
	v_div_fixup_f32 v234, v235, v234, v230
	ds_write_b32 v173, v234 offset:45760
	v_mul_f32_e32 v234, 0xbfb8aa3b, v231
	v_exp_f32_e32 v234, v234
	s_nop 0
	v_add_f32_e32 v234, 1.0, v234
	v_div_scale_f32 v235, s[4:5], v234, v234, v231
	v_rcp_f32_e32 v236, v235
	s_nop 0
	v_fma_f32 v237, -v235, v236, 1.0
	v_fmac_f32_e32 v236, v237, v236
	v_div_scale_f32 v237, vcc, v231, v234, v231
	v_mul_f32_e32 v238, v237, v236
	v_fma_f32 v239, -v235, v238, v237
	v_fmac_f32_e32 v238, v239, v236
	v_fma_f32 v235, -v235, v238, v237
	v_div_fmas_f32 v235, v235, v236, v238
	v_div_fixup_f32 v234, v235, v234, v231
	ds_write_b32 v173, v234 offset:46800
	v_mul_f32_e32 v234, 0xbfb8aa3b, v232
	v_exp_f32_e32 v234, v234
	s_nop 0
	v_add_f32_e32 v234, 1.0, v234
	v_div_scale_f32 v235, s[4:5], v234, v234, v232
	v_rcp_f32_e32 v236, v235
	s_nop 0
	v_fma_f32 v237, -v235, v236, 1.0
	v_fmac_f32_e32 v236, v237, v236
	v_div_scale_f32 v237, vcc, v232, v234, v232
	v_mul_f32_e32 v238, v237, v236
	v_fma_f32 v239, -v235, v238, v237
	v_fmac_f32_e32 v238, v239, v236
	v_fma_f32 v235, -v235, v238, v237
	v_div_fmas_f32 v235, v235, v236, v238
	v_div_fixup_f32 v234, v235, v234, v232
	ds_write_b32 v173, v234 offset:47840
	v_mul_f32_e32 v234, 0xbfb8aa3b, v233
	v_exp_f32_e32 v234, v234
	s_nop 0
	v_add_f32_e32 v234, 1.0, v234
	v_div_scale_f32 v235, s[4:5], v234, v234, v233
	v_rcp_f32_e32 v236, v235
	s_nop 0
	v_fma_f32 v237, -v235, v236, 1.0
	v_fmac_f32_e32 v236, v237, v236
	v_div_scale_f32 v237, vcc, v233, v234, v233
	v_mul_f32_e32 v238, v237, v236
	v_fma_f32 v239, -v235, v238, v237
	v_fmac_f32_e32 v238, v239, v236
	v_fma_f32 v235, -v235, v238, v237
	v_div_fmas_f32 v235, v235, v236, v238
	v_div_fixup_f32 v234, v235, v234, v233
	ds_write_b32 v173, v234 offset:48880
	s_waitcnt lgkmcnt(0)
	s_barrier
	s_and_saveexec_b64 s[88:89], s[38:39]
	s_cbranch_execz .LBB0_281
; DI void phase_gdn_prep(const Params& p, int l, char* smem) {
;     ...
;         const float bb = pbb, aa = paa;
;         if (tid < 64) {
;             const float xx = aa + p.dt_bias[l * 6 + h];
;             const float sp = xx > 20.f ? xx : log1pf(expf(xx));
	s_mul_i32 s4, s77, 6
	s_add_i32 s4, s6, s4
	s_ashr_i32 s5, s4, 31
	v_readlane_b32 s52, v251, 18
	s_lshl_b64 s[4:5], s[4:5], 2
	v_readlane_b32 s62, v251, 28
	v_readlane_b32 s63, v251, 29
	s_add_u32 s6, s62, s4
	s_addc_u32 s7, s63, s5
	v_mov_b32_e32 v0, v108
	s_mov_b32 s6, 0x41a00000
	v_readlane_b32 s53, v251, 19
	v_readlane_b32 s54, v251, 20
	v_readlane_b32 s55, v251, 21
	v_readlane_b32 s56, v251, 22
	v_readlane_b32 s57, v251, 23
	v_readlane_b32 s58, v251, 24
	v_readlane_b32 s59, v251, 25
	v_readlane_b32 s60, v251, 26
	v_readlane_b32 s61, v251, 27
	v_readlane_b32 s64, v251, 30
	v_readlane_b32 s65, v251, 31
	v_readlane_b32 s66, v251, 32
	v_readlane_b32 s67, v251, 33
	s_waitcnt vmcnt(0)
	v_add_f32_e32 v0, v49, v0
	v_cmp_nlt_f32_e32 vcc, s6, v0
	s_and_saveexec_b64 s[6:7], vcc
	s_cbranch_execz .LBB0_279
	v_mul_f32_e32 v1, 0x3fb8aa3b, v0
	v_rndne_f32_e32 v2, v1
	s_mov_b32 s2, 0x3fb8aa3b
	v_sub_f32_e32 v3, v1, v2
	v_fma_f32 v1, v0, s2, -v1
	v_fmac_f32_e32 v1, 0x32a5705f, v0
	v_add_f32_e32 v1, v3, v1
	v_cvt_i32_f32_e32 v2, v2
	v_exp_f32_e32 v1, v1
	s_mov_b32 s2, 0xc2ce8ed0
	v_cmp_ngt_f32_e32 vcc, s2, v0
	s_mov_b32 s2, 0x42b17218
	v_ldexp_f32 v1, v1, v2
	v_cndmask_b32_e32 v1, 0, v1, vcc
	v_cmp_nlt_f32_e32 vcc, s2, v0
	s_mov_b32 s8, 0x3f2aaaab
	s_nop 0
	v_cndmask_b32_e32 v14, v217, v1, vcc
	v_add_f32_e32 v2, 1.0, v14
	v_add_f32_e32 v0, -1.0, v2
	v_sub_f32_e32 v1, v0, v2
	v_add_f32_e32 v1, 1.0, v1
	v_sub_f32_e32 v0, v14, v0
	v_add_f32_e32 v3, v0, v1
	v_frexp_mant_f32_e32 v4, v2
	v_cvt_f64_f32_e32 v[0:1], v2
	v_frexp_exp_i32_f64_e32 v0, v[0:1]
	v_cmp_gt_f32_e32 vcc, s8, v4
	s_mov_b32 s8, 0x3f317218
	s_nop 0
	v_subbrev_co_u32_e32 v8, vcc, 0, v0, vcc
	v_sub_u32_e32 v0, 0, v8
	v_ldexp_f32 v1, v2, v0
	v_add_f32_e32 v2, -1.0, v1
	v_add_f32_e32 v4, 1.0, v1
	v_ldexp_f32 v0, v3, v0
	v_add_f32_e32 v3, 1.0, v2
	v_add_f32_e32 v5, -1.0, v4
	v_sub_f32_e32 v3, v1, v3
	v_sub_f32_e32 v1, v1, v5
	v_add_f32_e32 v3, v0, v3
	v_add_f32_e32 v0, v0, v1
	v_add_f32_e32 v9, v4, v0
	v_rcp_f32_e32 v11, v9
	v_sub_f32_e32 v1, v4, v9
	v_add_f32_e32 v10, v0, v1
	v_add_f32_e32 v1, v2, v3
	v_mul_f32_e32 v13, v1, v11
	v_sub_f32_e32 v0, v2, v1
	v_mul_f32_e32 v2, v9, v13
	v_fma_f32 v4, v13, v9, -v2
	v_fmac_f32_e32 v4, v13, v10
	v_add_f32_e32 v12, v3, v0
	v_add_f32_e32 v0, v2, v4
	v_sub_f32_e32 v3, v1, v0
	v_pk_add_f32 v[6:7], v[0:1], v[2:3] neg_lo:[0,1] neg_hi:[0,1]
	v_mov_b32_e32 v5, v0
	v_pk_add_f32 v[0:1], v[6:7], v[4:5] neg_lo:[0,1] neg_hi:[0,1]
	s_nop 0
	v_add_f32_e32 v1, v12, v1
	v_add_f32_e32 v0, v0, v1
	v_add_f32_e32 v1, v3, v0
	v_mul_f32_e32 v12, v11, v1
	v_mul_f32_e32 v2, v9, v12
	v_fma_f32 v4, v12, v9, -v2
	v_fmac_f32_e32 v4, v12, v10
	v_sub_f32_e32 v3, v3, v1
	v_add_f32_e32 v9, v0, v3
	v_add_f32_e32 v0, v2, v4
	v_sub_f32_e32 v3, v1, v0
	v_pk_add_f32 v[6:7], v[0:1], v[2:3] neg_lo:[0,1] neg_hi:[0,1]
	v_mov_b32_e32 v5, v0
	v_pk_add_f32 v[0:1], v[6:7], v[4:5] neg_lo:[0,1] neg_hi:[0,1]
	s_nop 0
	v_add_f32_e32 v1, v9, v1
	v_add_f32_e32 v0, v0, v1
	v_add_f32_e32 v1, v13, v12
	v_add_f32_e32 v0, v3, v0
	v_sub_f32_e32 v2, v1, v13
	v_mul_f32_e32 v0, v11, v0
	v_sub_f32_e32 v2, v12, v2
	v_add_f32_e32 v2, v2, v0
	v_add_f32_e32 v4, v1, v2
	v_mul_f32_e32 v5, v4, v4
	v_fmamk_f32 v0, v5, 0x3e9b6dac, v214
	v_fmaak_f32 v191, v5, v0, 0x3f2aaada
	v_cvt_f32_i32_e32 v0, v8
	v_sub_f32_e32 v1, v4, v1
	v_sub_f32_e32 v1, v2, v1
	v_ldexp_f32 v6, v1, 1
	v_mul_f32_e32 v1, v4, v5
	v_ldexp_f32 v3, v4, 1
	v_pk_mul_f32 v[4:5], v[0:1], v[190:191]
	s_nop 0
	v_fma_f32 v2, v0, s8, -v4
	v_fmac_f32_e32 v2, 0xb102e308, v0
	v_pk_add_f32 v[0:1], v[4:5], v[2:3]
	s_mov_b32 s8, 0x7f800000
	v_sub_f32_e32 v3, v1, v3
	v_sub_f32_e32 v3, v5, v3
	v_add_f32_e32 v7, v6, v3
	v_mov_b32_e32 v6, v4
	v_pk_add_f32 v[4:5], v[0:1], v[4:5] neg_lo:[0,1] neg_hi:[0,1]
	v_pk_add_f32 v[8:9], v[0:1], v[6:7]
	v_mov_b32_e32 v3, v0
	v_mov_b32_e32 v5, v9
	v_pk_add_f32 v[10:11], v[2:3], v[4:5] neg_lo:[0,1] neg_hi:[0,1]
	v_pk_add_f32 v[2:3], v[2:3], v[4:5]
	v_mov_b32_e32 v6, v7
	v_pk_add_f32 v[4:5], v[2:3], v[0:1] op_sel:[1,0] op_sel_hi:[0,1] neg_lo:[0,1] neg_hi:[0,1]
	v_pk_add_f32 v[12:13], v[8:9], v[4:5] op_sel_hi:[1,0] neg_lo:[0,1] neg_hi:[0,1]
	v_mov_b32_e32 v8, v9
	v_mov_b32_e32 v9, v3
	v_pk_mov_b32 v[4:5], v[0:1], v[4:5] op_sel:[1,0]
	v_mov_b32_e32 v7, v0
	v_pk_add_f32 v[4:5], v[8:9], v[4:5] neg_lo:[0,1] neg_hi:[0,1]
	v_mov_b32_e32 v12, v10
	v_pk_add_f32 v[0:1], v[6:7], v[4:5] neg_lo:[0,1] neg_hi:[0,1]
	v_mov_b32_e32 v11, v3
	v_pk_add_f32 v[4:5], v[12:13], v[0:1]
	v_cmp_neq_f32_e32 vcc, s8, v14
	v_pk_add_f32 v[6:7], v[4:5], v[4:5] op_sel:[0,1] op_sel_hi:[1,0]
	s_mov_b32 s8, 0x33800000
	v_pk_add_f32 v[2:3], v[2:3], v[6:7] op_sel:[1,0] op_sel_hi:[0,1]
	v_mov_b32_e32 v5, v2
	v_pk_add_f32 v[8:9], v[4:5], v[10:11] neg_lo:[0,1] neg_hi:[0,1]
	v_mov_b32_e32 v1, v6
	v_sub_f32_e32 v3, v4, v8
	v_pk_add_f32 v[0:1], v[0:1], v[8:9] neg_lo:[0,1] neg_hi:[0,1]
	v_sub_f32_e32 v3, v10, v3
	v_add_f32_e32 v0, v0, v3
	v_add_f32_e32 v0, v0, v1
	v_add_f32_e32 v0, v2, v0
	v_cndmask_b32_e32 v0, v217, v0, vcc
	v_cmp_lt_f32_e64 vcc, |v14|, s8
	s_nop 1
	v_cndmask_b32_e32 v0, v0, v14, vcc
; DI void phase_gdn_prep(const Params& p, int l, char* smem) {
;     ...
;             const float sp = xx > 20.f ? xx : log1pf(expf(xx));
;             float g = -expf(p.a_log[l * 6 + h]) * sp;
; #pragma unroll
;             for (int off = 1; off < 64; off <<= 1) { const float v = __shfl_up(g, off); if (lane >= off) g += v; }
;             sgc[tid] = g; sbeta[tid] = 1.f / (1.f + expf(-bb));
;             if (tid == 63) p.glast[item] = expf(g);
.LBB0_279:
	s_or_b64 exec, exec, s[6:7]
	v_readlane_b32 s52, v251, 18
	v_readlane_b32 s60, v251, 26
	v_readlane_b32 s61, v251, 27
	s_add_u32 s4, s60, s4
	s_addc_u32 s5, s61, s5
	v_mov_b32_e32 v1, v109
	s_mov_b32 s2, 0x3fb8aa3b
	v_readlane_b32 s4, v249, 36
	v_readlane_b32 s5, v249, 37
	v_readlane_b32 s53, v251, 19
	v_readlane_b32 s54, v251, 20
	v_readlane_b32 s55, v251, 21
	v_readlane_b32 s56, v251, 22
	v_readlane_b32 s57, v251, 23
	v_readlane_b32 s58, v251, 24
	v_readlane_b32 s59, v251, 25
	v_readlane_b32 s62, v251, 28
	v_readlane_b32 s63, v251, 29
	v_readlane_b32 s64, v251, 30
	v_readlane_b32 s65, v251, 31
	v_readlane_b32 s66, v251, 32
	v_readlane_b32 s67, v251, 33
	s_waitcnt vmcnt(0)
	v_mul_f32_e32 v2, 0x3fb8aa3b, v1
	v_fma_f32 v3, v1, s2, -v2
	v_rndne_f32_e32 v4, v2
	v_fmac_f32_e32 v3, 0x32a5705f, v1
	v_sub_f32_e32 v2, v2, v4
	v_add_f32_e32 v2, v2, v3
	v_exp_f32_e32 v2, v2
	v_cvt_i32_f32_e32 v3, v4
	s_mov_b32 s2, 0xc2ce8ed0
	v_cmp_ngt_f32_e32 vcc, s2, v1
	s_mov_b32 s2, 0x42b17218
	v_ldexp_f32 v2, v2, v3
	v_cndmask_b32_e32 v2, 0, v2, vcc
	v_cmp_nlt_f32_e32 vcc, s2, v1
	s_nop 1
	v_cndmask_b32_e32 v1, v217, v2, vcc
	v_mul_f32_e64 v2, v0, -v1
	ds_bpermute_b32 v3, v112, v2
	s_waitcnt lgkmcnt(0)
	v_fma_f32 v0, v0, -v1, v3
	v_cndmask_b32_e64 v0, v0, v2, s[4:5]
	ds_bpermute_b32 v1, v113, v0
	v_readlane_b32 s4, v249, 38
	v_readlane_b32 s5, v249, 39
	s_waitcnt lgkmcnt(0)
	v_add_f32_e32 v1, v0, v1
	v_cndmask_b32_e64 v0, v1, v0, s[4:5]
	ds_bpermute_b32 v1, v114, v0
	v_readlane_b32 s4, v249, 40
	v_readlane_b32 s5, v249, 41
	s_waitcnt lgkmcnt(0)
	v_add_f32_e32 v1, v0, v1
	v_cndmask_b32_e64 v0, v1, v0, s[4:5]
	ds_bpermute_b32 v1, v115, v0
	v_readlane_b32 s4, v249, 42
	v_readlane_b32 s5, v249, 43
	s_waitcnt lgkmcnt(0)
	v_add_f32_e32 v1, v0, v1
	v_cndmask_b32_e64 v0, v1, v0, s[4:5]
	ds_bpermute_b32 v1, v116, v0
	v_readlane_b32 s4, v249, 44
	v_readlane_b32 s5, v249, 45
	s_waitcnt lgkmcnt(0)
	v_add_f32_e32 v1, v0, v1
	v_cndmask_b32_e64 v1, v1, v0, s[4:5]
	ds_bpermute_b32 v0, v117, v1
	v_readlane_b32 s4, v249, 46
	v_readlane_b32 s5, v249, 47
	s_waitcnt lgkmcnt(0)
	v_add_f32_e32 v0, v1, v0
	v_cndmask_b32_e64 v1, v0, v1, s[4:5]
	ds_write_b32 v63, v1
	v_mul_f32_e32 v1, 0xbfb8aa3b, v55
	v_rndne_f32_e32 v2, v1
	s_mov_b32 s4, 0xbfb8aa3b
	v_sub_f32_e32 v3, v1, v2
	v_fma_f32 v1, v55, s4, -v1
	v_fmac_f32_e32 v1, 0xb2a5705f, v55
	v_add_f32_e32 v1, v3, v1
	v_exp_f32_e32 v1, v1
	v_cvt_i32_f32_e32 v2, v2
	s_mov_b32 s4, 0x42ce8ed0
	v_cmp_nlt_f32_e32 vcc, s4, v55
	s_mov_b32 s4, 0xc2b17218
	v_ldexp_f32 v1, v1, v2
	v_cndmask_b32_e32 v1, 0, v1, vcc
	v_cmp_ngt_f32_e32 vcc, s4, v55
	s_nop 1
	v_cndmask_b32_e32 v1, v217, v1, vcc
	v_add_f32_e32 v1, 1.0, v1
	v_div_scale_f32 v2, s[4:5], v1, v1, 1.0
	v_rcp_f32_e32 v3, v2
	v_readlane_b32 s4, v249, 34
	v_readlane_b32 s5, v249, 35
	v_fma_f32 v4, -v2, v3, 1.0
	v_fmac_f32_e32 v3, v4, v3
	v_div_scale_f32 v4, vcc, 1.0, v1, 1.0
	v_mul_f32_e32 v5, v4, v3
	v_fma_f32 v6, -v2, v5, v4
	v_fmac_f32_e32 v5, v6, v3
	v_fma_f32 v2, -v2, v5, v4
	v_div_fmas_f32 v2, v2, v3, v5
	v_div_fixup_f32 v1, v2, v1, 1.0
	ds_write_b32 v64, v1
	s_and_b64 exec, exec, s[4:5]
	s_cbranch_execz .LBB0_281
	v_mul_f32_e32 v1, 0x3fb8aa3b, v0
	v_rndne_f32_e32 v2, v1
	s_mov_b32 s2, 0x3fb8aa3b
	v_sub_f32_e32 v3, v1, v2
	v_fma_f32 v1, v0, s2, -v1
	v_fmac_f32_e32 v1, 0x32a5705f, v0
	v_add_f32_e32 v1, v3, v1
	v_exp_f32_e32 v1, v1
	v_cvt_i32_f32_e32 v2, v2
	v_readlane_b32 s52, v250, 51
	s_mov_b32 s2, 0xc2ce8ed0
	s_lshl_b64 s[4:5], s[86:87], 2
	v_readlane_b32 s62, v250, 61
	v_ldexp_f32 v1, v1, v2
	v_cmp_ngt_f32_e32 vcc, s2, v0
	s_mov_b32 s2, 0x42b17218
	v_readlane_b32 s63, v250, 62
	s_add_u32 s4, s62, s4
	v_cndmask_b32_e32 v1, 0, v1, vcc
	v_cmp_nlt_f32_e32 vcc, s2, v0
	s_addc_u32 s5, s63, s5
	v_readlane_b32 s53, v250, 52
	v_cndmask_b32_e32 v0, v217, v1, vcc
	v_readlane_b32 s54, v250, 53
	v_readlane_b32 s55, v250, 54
	v_readlane_b32 s56, v250, 55
	v_readlane_b32 s57, v250, 56
	v_readlane_b32 s58, v250, 57
	v_readlane_b32 s59, v250, 58
	v_readlane_b32 s60, v250, 59
	v_readlane_b32 s61, v250, 60
	v_readlane_b32 s64, v250, 63
	v_readlane_b32 s65, v249, 0
	v_readlane_b32 s66, v249, 1
	v_readlane_b32 s67, v249, 2
	global_store_dword v189, v0, s[4:5]
